# prep phase: leftover lora2 single trips and vat items moved off the workgroups that carry the extra prep row
# speedup vs baseline: 1.0110x; 1.0110x over previous
.LBB0_443:
	s_ashr_i32 s43, s42, 31
	v_lshl_add_u64 v[24:25], s[42:43], 1, v[8:9]
	ds_read_b128 v[8:11], v2
	ds_read_b128 v[12:15], v2 offset:16
	ds_read_b128 v[16:19], v2 offset:32
	ds_read_b128 v[20:23], v2 offset:48
	s_add_i32 s2, s2, s4
	s_cmpk_lg_i32 s4, 0x800
	s_cbranch_scc1 .Lvat_rot_ok
	s_addk_i32 s2, 0x400
	s_cmpk_lt_i32 s2, 0x1000
	s_cbranch_scc1 .Lvat_rot_ok
	s_sub_i32 s2, s2, s4
.Lvat_rot_ok:
	s_cmpk_lt_i32 s2, 0x850
	s_waitcnt lgkmcnt(3)
	global_store_dwordx4 v[24:25], v[8:11], off
	s_waitcnt lgkmcnt(2)
	global_store_dwordx4 v[24:25], v[12:15], off offset:16
	s_waitcnt lgkmcnt(1)
	global_store_dwordx4 v[24:25], v[16:19], off offset:32
	s_waitcnt lgkmcnt(0)
	global_store_dwordx4 v[24:25], v[20:23], off offset:48
	ds_read_b128 v[8:11], v2 offset:64
	s_waitcnt lgkmcnt(0)
	global_store_dwordx4 v[24:25], v[8:11], off offset:64
	ds_read_b128 v[8:11], v2 offset:80
	s_waitcnt lgkmcnt(0)
	global_store_dwordx4 v[24:25], v[8:11], off offset:80
	ds_read_b128 v[8:11], v2 offset:96
	s_waitcnt lgkmcnt(0)
	global_store_dwordx4 v[24:25], v[8:11], off offset:96
	ds_read_b128 v[8:11], v2 offset:112
	s_waitcnt lgkmcnt(0)
	global_store_dwordx4 v[24:25], v[8:11], off offset:112
	s_waitcnt lgkmcnt(0)
	s_cbranch_scc0 .LBB0_451

.LBB0_454:
	s_waitcnt vmcnt(11)
	v_mfma_f32_16x16x32_bf16 v[52:55], v[76:79], v[0:3], 0
	v_ashrrev_i32_e32 v191, 31, v190
	v_lshlrev_b64 v[116:117], 2, v[190:191]
	v_lshl_add_u64 v[64:65], s[44:45], 0, v[116:117]
	s_waitcnt vmcnt(10)
	v_mfma_f32_16x16x32_bf16 v[118:121], v[80:83], v[8:11], v[52:55]
	v_lshl_add_u64 v[224:225], s[74:75], 0, v[194:195]
	s_mov_b32 s6, 0x30f00000
	v_or_b32_e32 v138, 0x400, v196
	s_waitcnt vmcnt(5)
	v_mfma_f32_16x16x32_bf16 v[52:55], v[88:91], v[0:3], 0
	v_mov_b32_e32 v139, v197
	s_nop 1
	v_add_f32_e32 v96, v96, v118
	v_add_f32_e32 v97, v97, v119
	s_waitcnt vmcnt(4)
	v_mfma_f32_16x16x32_bf16 v[122:125], v[92:95], v[8:11], v[52:55]
	v_lshl_add_u64 v[92:93], s[74:75], 0, v[204:205]
	v_add_f32_e32 v98, v98, v120
	v_add_f32_e32 v99, v99, v121
	s_waitcnt vmcnt(3)
	v_mfma_f32_16x16x32_bf16 v[52:55], v[100:103], v[0:3], 0
	v_mul_f32_e32 v96, 0xbfb8aa3b, v96
	s_nop 1
	v_add_f32_e32 v84, v84, v122
	v_add_f32_e32 v85, v85, v123
	s_waitcnt vmcnt(2)
	v_mfma_f32_16x16x32_bf16 v[126:129], v[104:107], v[8:11], v[52:55]
	v_lshl_add_u64 v[104:105], s[74:75], 0, v[218:219]
	v_mul_f32_e32 v97, 0xbfb8aa3b, v97
	v_mul_f32_e32 v98, 0xbfb8aa3b, v98
	s_waitcnt vmcnt(1)
	v_mfma_f32_16x16x32_bf16 v[52:55], v[108:111], v[0:3], 0
	v_mul_f32_e32 v99, 0xbfb8aa3b, v99
	s_nop 1
	v_add_f32_e32 v72, v72, v126
	v_add_f32_e32 v73, v73, v127
	s_waitcnt vmcnt(0)
	v_mfma_f32_16x16x32_bf16 v[130:133], v[112:115], v[8:11], v[52:55]
	v_lshl_add_u64 v[112:113], s[74:75], 0, v[222:223]
	v_add_f32_e32 v74, v74, v128
	v_add_f32_e32 v75, v75, v129
	v_lshl_add_u64 v[52:53], s[74:75], 0, v[198:199]
	global_load_dwordx4 v[76:79], v[52:53], off
	global_load_dwordx4 v[80:83], v[52:53], off offset:64
	s_nop 0
	global_load_dwordx4 v[52:55], v[64:65], off offset:48
	global_load_dwordx4 v[56:59], v[64:65], off offset:32
	global_load_dwordx4 v[60:63], v[64:65], off offset:16
	s_nop 0
	global_load_dwordx4 v[64:67], v[64:65], off
	s_nop 0
	global_load_dwordx4 v[88:91], v[92:93], off
	s_nop 0
	global_load_dwordx4 v[92:95], v[92:93], off offset:64
	s_nop 0
	global_load_dwordx4 v[100:103], v[104:105], off
	s_nop 0
	global_load_dwordx4 v[104:107], v[104:105], off offset:64
	s_nop 0
	global_load_dwordx4 v[108:111], v[112:113], off
	s_nop 0
	global_load_dwordx4 v[112:115], v[112:113], off offset:64
	v_add_f32_e32 v68, v68, v130
	v_add_f32_e32 v69, v69, v131
	v_add_f32_e32 v70, v70, v132
	v_add_f32_e32 v71, v71, v133
	v_mul_f32_e32 v72, 0xbfb8aa3b, v72
	v_mul_f32_e32 v73, 0xbfb8aa3b, v73
	v_mul_f32_e32 v74, 0xbfb8aa3b, v74
	v_mul_f32_e32 v75, 0xbfb8aa3b, v75
	v_mul_f32_e32 v68, 0xbfb8aa3b, v68
	v_mul_f32_e32 v69, 0xbfb8aa3b, v69
	v_mul_f32_e32 v70, 0xbfb8aa3b, v70
	v_mul_f32_e32 v71, 0xbfb8aa3b, v71
	v_exp_f32_e32 v72, v72
	v_exp_f32_e32 v73, v73
	v_exp_f32_e32 v74, v74
	v_exp_f32_e32 v75, v75
	v_exp_f32_e32 v68, v68
	v_exp_f32_e32 v69, v69
	v_exp_f32_e32 v70, v70
	v_exp_f32_e32 v71, v71
	v_mul_f32_e32 v84, 0xbfb8aa3b, v84
	v_mul_f32_e32 v85, 0xbfb8aa3b, v85
	v_add_f32_e32 v86, v86, v124
	v_add_f32_e32 v87, v87, v125
	v_exp_f32_e32 v96, v96
	v_exp_f32_e32 v97, v97
	v_exp_f32_e32 v98, v98
	v_exp_f32_e32 v99, v99
	v_exp_f32_e32 v84, v84
	v_exp_f32_e32 v85, v85
	v_mul_f32_e32 v86, 0xbfb8aa3b, v86
	v_mul_f32_e32 v87, 0xbfb8aa3b, v87
	v_exp_f32_e32 v86, v86
	v_exp_f32_e32 v87, v87
	v_add_f32_e32 v72, 1.0, v72
	v_add_f32_e32 v73, 1.0, v73
	v_add_f32_e32 v74, 1.0, v74
	v_add_f32_e32 v75, 1.0, v75
	v_add_f32_e32 v68, 1.0, v68
	v_add_f32_e32 v69, 1.0, v69
	v_add_f32_e32 v70, 1.0, v70
	v_add_f32_e32 v71, 1.0, v71
	v_rcp_f32_e32 v72, v72
	v_rcp_f32_e32 v73, v73
	v_rcp_f32_e32 v74, v74
	v_rcp_f32_e32 v75, v75
	v_rcp_f32_e32 v68, v68
	v_rcp_f32_e32 v69, v69
	v_rcp_f32_e32 v70, v70
	v_rcp_f32_e32 v71, v71
	v_add_f32_e32 v96, 1.0, v96
	v_add_f32_e32 v97, 1.0, v97
	v_add_f32_e32 v98, 1.0, v98
	v_add_f32_e32 v99, 1.0, v99
	v_add_f32_e32 v84, 1.0, v84
	v_add_f32_e32 v85, 1.0, v85
	v_rcp_f32_e32 v96, v96
	v_rcp_f32_e32 v97, v97
	v_rcp_f32_e32 v98, v98
	v_rcp_f32_e32 v99, v99
	v_rcp_f32_e32 v84, v84
	v_rcp_f32_e32 v85, v85
	v_add_f32_e32 v86, 1.0, v86
	v_add_f32_e32 v87, 1.0, v87
	v_rcp_f32_e32 v86, v86
	v_rcp_f32_e32 v87, v87
	v_pk_mul_f32 v[72:73], v[72:73], s[76:77] op_sel_hi:[1,0]
	v_pk_mul_f32 v[74:75], v[74:75], s[76:77] op_sel_hi:[1,0]
	v_pk_mul_f32 v[68:69], v[68:69], s[76:77] op_sel_hi:[1,0]
	v_pk_mul_f32 v[70:71], v[70:71], s[76:77] op_sel_hi:[1,0]
	v_cvt_pk_bf16_f32 v72, v72, v73
	v_cvt_pk_bf16_f32 v73, v74, v75
	v_cvt_pk_bf16_f32 v74, v68, v69
	v_cvt_pk_bf16_f32 v75, v70, v71
	s_waitcnt vmcnt(11)
	v_mfma_f32_16x16x32_bf16 v[68:71], v[76:79], v[4:7], 0
	v_mul_f32_e64 v96, v96, s76
	v_mul_f32_e64 v97, v97, s76
	v_pk_mul_f32 v[98:99], v[98:99], s[76:77] op_sel_hi:[1,0]
	v_pk_mul_f32 v[84:85], v[84:85], s[76:77] op_sel_hi:[1,0]
	v_pk_mul_f32 v[86:87], v[86:87], s[76:77] op_sel_hi:[1,0]
	v_cvt_pk_bf16_f32 v96, v96, v97
	v_cvt_pk_bf16_f32 v97, v98, v99
	v_cvt_pk_bf16_f32 v98, v84, v85
	v_add_co_u32_e32 v84, vcc, s6, v224
	v_cvt_pk_bf16_f32 v99, v86, v87
	s_nop 0
	v_addc_co_u32_e32 v85, vcc, 0, v225, vcc
	global_store_dwordx4 v[84:85], v[96:99], off
	s_mov_b32 s6, 0x44900000
	global_store_dwordx4 v[84:85], v[72:75], off offset:16
	s_waitcnt vmcnt(12)
	v_mfma_f32_16x16x32_bf16 v[96:99], v[80:83], v[12:15], v[68:71]
	v_lshl_add_u64 v[80:81], s[48:49], 0, v[116:117]
	v_lshl_add_u64 v[126:127], v[168:169], 0, v[138:139]
	s_waitcnt vmcnt(7)
	v_mfma_f32_16x16x32_bf16 v[68:71], v[88:91], v[4:7], 0
	v_lshl_add_u64 v[88:89], s[74:75], 0, v[200:201]
	v_or_b32_e32 v90, 0x200, v196
	v_mov_b32_e32 v91, v197
	s_waitcnt vmcnt(6)
	v_mfma_f32_16x16x32_bf16 v[92:95], v[92:95], v[12:15], v[68:71]
	v_lshl_add_u64 v[118:119], v[168:169], 0, v[90:91]
	v_or_b32_e32 v140, 0x600, v196
	v_mov_b32_e32 v141, v197
	s_waitcnt vmcnt(5)
	v_mfma_f32_16x16x32_bf16 v[68:71], v[100:103], v[4:7], 0
	v_lshl_add_u64 v[134:135], v[168:169], 0, v[140:141]
	s_nop 1
	v_add_f32_e32 v60, v60, v92
	v_add_f32_e32 v61, v61, v93
	s_waitcnt vmcnt(4)
	v_mfma_f32_16x16x32_bf16 v[100:103], v[104:107], v[12:15], v[68:71]
	v_add_f32_e32 v64, v64, v96
	v_add_f32_e32 v65, v65, v97
	v_add_f32_e32 v66, v66, v98
	s_waitcnt vmcnt(3)
	v_mfma_f32_16x16x32_bf16 v[68:71], v[108:111], v[4:7], 0
	v_add_f32_e32 v67, v67, v99
	s_nop 1
	v_add_f32_e32 v56, v56, v100
	v_mul_f32_e32 v56, 0xbfb8aa3b, v56
	s_waitcnt vmcnt(2)
	v_mfma_f32_16x16x32_bf16 v[84:87], v[112:115], v[12:15], v[68:71]
	v_exp_f32_e32 v56, v56
	v_add_f32_e32 v62, v62, v94
	v_add_f32_e32 v63, v63, v95
	v_add_co_u32_e32 v68, vcc, s6, v88
	v_add_f32_e32 v56, 1.0, v56
	s_nop 0
	v_addc_co_u32_e32 v69, vcc, 0, v89, vcc
	global_load_dwordx4 v[104:107], v[68:69], off
	global_load_dwordx4 v[108:111], v[68:69], off offset:64
	s_nop 0
	global_load_dwordx4 v[68:71], v[80:81], off offset:48
	global_load_dwordx4 v[72:75], v[80:81], off offset:32
	global_load_dwordx4 v[76:79], v[80:81], off offset:16
	s_nop 0
	global_load_dwordx4 v[80:83], v[80:81], off
	s_nop 0
	global_load_dwordx4 v[112:115], v[118:119], off
	s_nop 0
	global_load_dwordx4 v[118:121], v[118:119], off offset:64
	s_nop 0
	global_load_dwordx4 v[122:125], v[126:127], off
	s_nop 0
	global_load_dwordx4 v[126:129], v[126:127], off offset:64
	s_nop 0
	global_load_dwordx4 v[130:133], v[134:135], off
	s_nop 0
	global_load_dwordx4 v[134:137], v[134:135], off offset:64
	v_add_f32_e32 v52, v52, v84
	v_mul_f32_e32 v52, 0xbfb8aa3b, v52
	v_exp_f32_e32 v52, v52
	v_rcp_f32_e32 v92, v56
	v_add_f32_e32 v56, v57, v101
	v_mul_f32_e32 v56, 0xbfb8aa3b, v56
	v_add_f32_e32 v52, 1.0, v52
	v_rcp_f32_e32 v84, v52
	v_add_f32_e32 v52, v53, v85
	v_mul_f32_e32 v52, 0xbfb8aa3b, v52
	v_exp_f32_e32 v56, v56
	v_exp_f32_e32 v52, v52
	v_mul_f32_e32 v64, 0xbfb8aa3b, v64
	v_mul_f32_e32 v65, 0xbfb8aa3b, v65
	v_add_f32_e32 v56, 1.0, v56
	v_add_f32_e32 v52, 1.0, v52
	v_rcp_f32_e32 v93, v56
	v_add_f32_e32 v56, v58, v102
	v_rcp_f32_e32 v85, v52
	v_add_f32_e32 v52, v54, v86
	v_mul_f32_e32 v56, 0xbfb8aa3b, v56
	v_mul_f32_e32 v52, 0xbfb8aa3b, v52
	v_exp_f32_e32 v56, v56
	v_exp_f32_e32 v52, v52
	v_mul_f32_e32 v66, 0xbfb8aa3b, v66
	v_mul_f32_e32 v67, 0xbfb8aa3b, v67
	v_add_f32_e32 v56, 1.0, v56
	v_add_f32_e32 v52, 1.0, v52
	v_mul_f32_e32 v60, 0xbfb8aa3b, v60
	v_mul_f32_e32 v61, 0xbfb8aa3b, v61
	v_mul_f32_e32 v62, 0xbfb8aa3b, v62
	v_mul_f32_e32 v63, 0xbfb8aa3b, v63
	v_rcp_f32_e32 v58, v56
	v_add_f32_e32 v56, v59, v103
	v_rcp_f32_e32 v86, v52
	v_add_f32_e32 v52, v55, v87
	v_exp_f32_e32 v64, v64
	v_exp_f32_e32 v65, v65
	v_exp_f32_e32 v66, v66
	v_exp_f32_e32 v67, v67
	v_exp_f32_e32 v60, v60
	v_exp_f32_e32 v61, v61
	v_exp_f32_e32 v62, v62
	v_exp_f32_e32 v63, v63
	v_mul_f32_e32 v56, 0xbfb8aa3b, v56
	v_mul_f32_e32 v52, 0xbfb8aa3b, v52
	v_exp_f32_e32 v56, v56
	v_exp_f32_e32 v52, v52
	v_add_f32_e32 v64, 1.0, v64
	v_add_f32_e32 v65, 1.0, v65
	v_add_f32_e32 v66, 1.0, v66
	v_add_f32_e32 v67, 1.0, v67
	v_add_f32_e32 v60, 1.0, v60
	v_add_f32_e32 v61, 1.0, v61
	v_add_f32_e32 v62, 1.0, v62
	v_add_f32_e32 v63, 1.0, v63
	v_rcp_f32_e32 v64, v64
	v_rcp_f32_e32 v65, v65
	v_rcp_f32_e32 v66, v66
	v_rcp_f32_e32 v67, v67
	v_rcp_f32_e32 v60, v60
	v_rcp_f32_e32 v61, v61
	v_rcp_f32_e32 v62, v62
	v_rcp_f32_e32 v63, v63
	v_add_f32_e32 v56, 1.0, v56
	v_add_f32_e32 v52, 1.0, v52
	v_rcp_f32_e32 v59, v56
	v_rcp_f32_e32 v87, v52
	v_add_co_u32_e32 v56, vcc, s97, v224
	v_cvt_pk_bf16_f32 v52, v64, v65
	v_cvt_pk_bf16_f32 v53, v66, v67
	v_cvt_pk_bf16_f32 v54, v60, v61
	v_cvt_pk_bf16_f32 v55, v62, v63
	v_addc_co_u32_e32 v57, vcc, 0, v225, vcc
	global_store_dwordx4 v[56:57], v[52:55], off
	s_mov_b32 s6, 0x44a00000
	v_lshl_add_u64 v[64:65], s[50:51], 0, v[116:117]
	v_cvt_pk_bf16_f32 v52, v92, v93
	v_cvt_pk_bf16_f32 v53, v58, v59
	v_cvt_pk_bf16_f32 v54, v84, v85
	v_cvt_pk_bf16_f32 v55, v86, v87
	global_store_dwordx4 v[56:57], v[52:55], off offset:16
	v_lshl_add_u64 v[160:161], s[74:75], 0, v[216:217]
	s_add_i32 s4, s10, 1
	s_waitcnt vmcnt(13)
	v_mfma_f32_16x16x32_bf16 v[52:55], v[104:107], v[16:19], 0
	s_cmp_lt_u32 s4, s60
	s_cselect_b32 s5, s4, s10
	s_lshl_b32 s5, s5, 6
	s_waitcnt vmcnt(12)
	v_mfma_f32_16x16x32_bf16 v[84:87], v[108:111], v[24:27], v[52:55]
	s_add_i32 s5, s5, s2
	s_cmp_ge_u32 s4, s60
	v_lshl_add_u64 v[194:195], v[194:195], 0, s[34:35]
	s_waitcnt vmcnt(7)
	v_mfma_f32_16x16x32_bf16 v[52:55], v[112:115], v[16:19], 0
	v_lshl_add_u64 v[112:113], v[170:171], 0, v[90:91]
	s_nop 1
	v_add_f32_e32 v80, v80, v84
	v_add_f32_e32 v81, v81, v85
	s_waitcnt vmcnt(6)
	v_mfma_f32_16x16x32_bf16 v[92:95], v[118:121], v[24:27], v[52:55]
	v_lshl_add_u64 v[120:121], v[170:171], 0, v[138:139]
	v_add_f32_e32 v82, v82, v86
	v_add_f32_e32 v83, v83, v87
	s_waitcnt vmcnt(5)
	v_mfma_f32_16x16x32_bf16 v[52:55], v[122:125], v[16:19], 0
	v_mul_f32_e32 v80, 0xbfb8aa3b, v80
	s_nop 1
	v_add_f32_e32 v76, v76, v92
	v_add_f32_e32 v77, v77, v93
	s_waitcnt vmcnt(4)
	v_mfma_f32_16x16x32_bf16 v[96:99], v[126:129], v[24:27], v[52:55]
	v_lshl_add_u64 v[128:129], v[170:171], 0, v[140:141]
	v_mul_f32_e32 v76, 0xbfb8aa3b, v76
	v_mul_f32_e32 v77, 0xbfb8aa3b, v77
	s_waitcnt vmcnt(3)
	v_mfma_f32_16x16x32_bf16 v[52:55], v[130:133], v[16:19], 0
	v_add_f32_e32 v78, v78, v94
	v_add_f32_e32 v79, v79, v95
	v_mul_f32_e32 v81, 0xbfb8aa3b, v81
	s_waitcnt vmcnt(2)
	v_mfma_f32_16x16x32_bf16 v[100:103], v[134:137], v[24:27], v[52:55]
	v_mul_f32_e32 v82, 0xbfb8aa3b, v82
	v_mul_f32_e32 v83, 0xbfb8aa3b, v83
	v_exp_f32_e32 v76, v76
	v_add_co_u32_e32 v52, vcc, s6, v88
	v_exp_f32_e32 v77, v77
	s_nop 0
	v_addc_co_u32_e32 v53, vcc, 0, v89, vcc
	global_load_dwordx4 v[104:107], v[52:53], off
	global_load_dwordx4 v[108:111], v[52:53], off offset:64
	s_nop 0
	global_load_dwordx4 v[52:55], v[64:65], off offset:48
	global_load_dwordx4 v[56:59], v[64:65], off offset:32
	global_load_dwordx4 v[60:63], v[64:65], off offset:16
	s_nop 0
	global_load_dwordx4 v[64:67], v[64:65], off
	s_nop 0
	global_load_dwordx4 v[88:91], v[112:113], off
	s_nop 0
	global_load_dwordx4 v[112:115], v[112:113], off offset:64
	s_nop 0
	global_load_dwordx4 v[116:119], v[120:121], off
	s_nop 0
	global_load_dwordx4 v[120:123], v[120:121], off offset:64
	s_nop 0
	global_load_dwordx4 v[124:127], v[128:129], off
	s_nop 0
	global_load_dwordx4 v[128:131], v[128:129], off offset:64
	v_add_f32_e32 v68, v68, v100
	v_add_f32_e32 v69, v69, v101
	v_mul_f32_e32 v68, 0xbfb8aa3b, v68
	v_mul_f32_e32 v69, 0xbfb8aa3b, v69
	v_exp_f32_e32 v68, v68
	v_exp_f32_e32 v69, v69
	v_mul_f32_e32 v78, 0xbfb8aa3b, v78
	v_mul_f32_e32 v79, 0xbfb8aa3b, v79
	v_add_f32_e32 v68, 1.0, v68
	v_add_f32_e32 v69, 1.0, v69
	v_rcp_f32_e32 v68, v68
	v_rcp_f32_e32 v69, v69
	v_add_f32_e32 v72, v72, v96
	v_add_f32_e32 v73, v73, v97
	v_add_f32_e32 v74, v74, v98
	v_add_f32_e32 v75, v75, v99
	v_pk_mul_f32 v[84:85], v[68:69], s[76:77] op_sel_hi:[1,0]
	v_add_f32_e32 v68, v70, v102
	v_add_f32_e32 v69, v71, v103
	v_exp_f32_e32 v80, v80
	v_exp_f32_e32 v81, v81
	v_exp_f32_e32 v82, v82
	v_exp_f32_e32 v83, v83
	v_exp_f32_e32 v78, v78
	v_exp_f32_e32 v79, v79
	v_mul_f32_e32 v72, 0xbfb8aa3b, v72
	v_mul_f32_e32 v73, 0xbfb8aa3b, v73
	v_mul_f32_e32 v74, 0xbfb8aa3b, v74
	v_mul_f32_e32 v75, 0xbfb8aa3b, v75
	v_mul_f32_e32 v68, 0xbfb8aa3b, v68
	v_mul_f32_e32 v69, 0xbfb8aa3b, v69
	v_exp_f32_e32 v72, v72
	v_exp_f32_e32 v73, v73
	v_exp_f32_e32 v74, v74
	v_exp_f32_e32 v75, v75
	v_exp_f32_e32 v68, v68
	v_exp_f32_e32 v69, v69
	v_add_f32_e32 v76, 1.0, v76
	v_add_f32_e32 v77, 1.0, v77
	v_add_f32_e32 v80, 1.0, v80
	v_add_f32_e32 v81, 1.0, v81
	v_add_f32_e32 v82, 1.0, v82
	v_add_f32_e32 v83, 1.0, v83
	v_rcp_f32_e32 v76, v76
	v_rcp_f32_e32 v77, v77
	v_add_f32_e32 v78, 1.0, v78
	v_add_f32_e32 v79, 1.0, v79
	v_rcp_f32_e32 v80, v80
	v_rcp_f32_e32 v81, v81
	v_rcp_f32_e32 v82, v82
	v_rcp_f32_e32 v83, v83
	v_rcp_f32_e32 v78, v78
	v_rcp_f32_e32 v79, v79
	v_add_f32_e32 v72, 1.0, v72
	v_add_f32_e32 v73, 1.0, v73
	v_add_f32_e32 v74, 1.0, v74
	v_add_f32_e32 v75, 1.0, v75
	v_add_f32_e32 v68, 1.0, v68
	v_add_f32_e32 v69, 1.0, v69
	v_rcp_f32_e32 v72, v72
	v_rcp_f32_e32 v73, v73
	v_rcp_f32_e32 v74, v74
	v_rcp_f32_e32 v75, v75
	v_rcp_f32_e32 v68, v68
	v_rcp_f32_e32 v69, v69
	v_pk_mul_f32 v[76:77], v[76:77], s[76:77] op_sel_hi:[1,0]
	s_mov_b32 s6, 0x33000000
	v_pk_mul_f32 v[80:81], v[80:81], s[76:77] op_sel_hi:[1,0]
	v_pk_mul_f32 v[82:83], v[82:83], s[76:77] op_sel_hi:[1,0]
	v_pk_mul_f32 v[78:79], v[78:79], s[76:77] op_sel_hi:[1,0]
	v_cvt_pk_bf16_f32 v70, v76, v77
	v_add_co_u32_e32 v76, vcc, s6, v224
	v_pk_mul_f32 v[72:73], v[72:73], s[76:77] op_sel_hi:[1,0]
	v_pk_mul_f32 v[74:75], v[74:75], s[76:77] op_sel_hi:[1,0]
	v_pk_mul_f32 v[86:87], v[68:69], s[76:77] op_sel_hi:[1,0]
	v_cvt_pk_bf16_f32 v68, v80, v81
	v_cvt_pk_bf16_f32 v69, v82, v83
	v_cvt_pk_bf16_f32 v71, v78, v79
	v_addc_co_u32_e32 v77, vcc, 0, v225, vcc
	global_store_dwordx4 v[76:77], v[68:71], off
	v_lshl_add_u64 v[100:101], s[74:75], 0, v[202:203]
	v_lshl_add_u64 v[140:141], s[74:75], 0, v[220:221]
	v_cvt_pk_bf16_f32 v68, v72, v73
	v_cvt_pk_bf16_f32 v69, v74, v75
	v_cvt_pk_bf16_f32 v70, v84, v85
	v_cvt_pk_bf16_f32 v71, v86, v87
	global_store_dwordx4 v[76:77], v[68:71], off offset:16
	v_lshl_add_u64 v[196:197], v[196:197], 0, s[18:19]
	v_lshl_add_u64 v[198:199], v[198:199], 0, s[18:19]
	s_waitcnt vmcnt(13)
	v_mfma_f32_16x16x32_bf16 v[68:71], v[104:107], v[20:23], 0
	v_lshl_add_u64 v[200:201], v[200:201], 0, s[18:19]
	v_lshl_add_u64 v[202:203], v[202:203], 0, s[22:23]
	v_lshl_add_u64 v[204:205], v[204:205], 0, s[18:19]
	s_waitcnt vmcnt(12)
	v_mfma_f32_16x16x32_bf16 v[80:83], v[108:111], v[28:31], v[68:71]
	v_lshl_add_u64 v[216:217], v[216:217], 0, s[22:23]
	v_lshl_add_u64 v[218:219], v[218:219], 0, s[18:19]
	v_lshl_add_u64 v[220:221], v[220:221], 0, s[22:23]
	s_waitcnt vmcnt(7)
	v_mfma_f32_16x16x32_bf16 v[68:71], v[88:91], v[20:23], 0
	global_load_dwordx4 v[84:87], v[100:101], off offset:-128
	global_load_dwordx4 v[88:91], v[100:101], off offset:-64
	global_load_dwordx4 v[92:95], v[100:101], off
	global_load_dwordx4 v[96:99], v[100:101], off offset:64
	s_nop 0
	global_load_dwordx4 v[100:103], v[100:101], off offset:128
	v_add_f32_e32 v64, v64, v80
	v_add_f32_e32 v65, v65, v81
	s_waitcnt vmcnt(11)
	v_mfma_f32_16x16x32_bf16 v[76:79], v[112:115], v[28:31], v[68:71]
	v_add_f32_e32 v66, v66, v82
	v_add_f32_e32 v67, v67, v83
	v_mul_f32_e32 v64, 0xbfb8aa3b, v64
	s_waitcnt vmcnt(10)
	v_mfma_f32_16x16x32_bf16 v[68:71], v[116:119], v[20:23], 0
	v_mul_f32_e32 v65, 0xbfb8aa3b, v65
	s_nop 1
	v_add_f32_e32 v60, v60, v76
	v_add_f32_e32 v61, v61, v77
	s_waitcnt vmcnt(9)
	v_mfma_f32_16x16x32_bf16 v[72:75], v[120:123], v[28:31], v[68:71]
	v_lshl_add_u64 v[120:121], s[74:75], 0, v[206:207]
	global_load_dwordx4 v[104:107], v[120:121], off offset:-128
	global_load_dwordx4 v[108:111], v[120:121], off offset:-64
	global_load_dwordx4 v[112:115], v[120:121], off
	global_load_dwordx4 v[116:119], v[120:121], off offset:64
	s_nop 0
	global_load_dwordx4 v[120:123], v[120:121], off offset:128
	v_mul_f32_e32 v60, 0xbfb8aa3b, v60
	s_waitcnt vmcnt(13)
	v_mfma_f32_16x16x32_bf16 v[68:71], v[124:127], v[20:23], 0
	v_mul_f32_e32 v61, 0xbfb8aa3b, v61
	v_add_f32_e32 v62, v62, v78
	v_add_f32_e32 v63, v63, v79
	s_waitcnt vmcnt(12)
	v_mfma_f32_16x16x32_bf16 v[68:71], v[128:131], v[28:31], v[68:71]
	v_mul_f32_e32 v66, 0xbfb8aa3b, v66
	v_mul_f32_e32 v67, 0xbfb8aa3b, v67
	v_exp_f32_e32 v60, v60
	v_exp_f32_e32 v61, v61
	v_mul_f32_e32 v62, 0xbfb8aa3b, v62
	s_nop 2
	v_add_f32_e32 v52, v52, v68
	v_mul_f32_e32 v52, 0xbfb8aa3b, v52
	v_exp_f32_e32 v52, v52
	v_mul_f32_e32 v63, 0xbfb8aa3b, v63
	v_add_f32_e32 v56, v56, v72
	v_add_f32_e32 v57, v57, v73
	v_add_f32_e32 v52, 1.0, v52
	v_rcp_f32_e32 v68, v52
	v_add_f32_e32 v52, v53, v69
	v_mul_f32_e32 v52, 0xbfb8aa3b, v52
	v_exp_f32_e32 v52, v52
	v_add_f32_e32 v58, v58, v74
	v_add_f32_e32 v59, v59, v75
	v_exp_f32_e32 v64, v64
	v_add_f32_e32 v52, 1.0, v52
	v_rcp_f32_e32 v69, v52
	v_add_f32_e32 v52, v54, v70
	v_mul_f32_e32 v52, 0xbfb8aa3b, v52
	v_exp_f32_e32 v52, v52
	v_exp_f32_e32 v65, v65
	v_exp_f32_e32 v66, v66
	v_exp_f32_e32 v67, v67
	v_add_f32_e32 v52, 1.0, v52
	v_rcp_f32_e32 v70, v52
	v_add_f32_e32 v52, v55, v71
	v_exp_f32_e32 v62, v62
	v_exp_f32_e32 v63, v63
	v_mul_f32_e32 v56, 0xbfb8aa3b, v56
	v_mul_f32_e32 v57, 0xbfb8aa3b, v57
	v_mul_f32_e32 v58, 0xbfb8aa3b, v58
	v_mul_f32_e32 v59, 0xbfb8aa3b, v59
	v_mul_f32_e32 v52, 0xbfb8aa3b, v52
	v_exp_f32_e32 v56, v56
	v_exp_f32_e32 v57, v57
	v_exp_f32_e32 v58, v58
	v_exp_f32_e32 v59, v59
	v_exp_f32_e32 v52, v52
	v_add_f32_e32 v60, 1.0, v60
	v_add_f32_e32 v61, 1.0, v61
	v_add_f32_e32 v64, 1.0, v64
	v_add_f32_e32 v65, 1.0, v65
	v_add_f32_e32 v66, 1.0, v66
	v_add_f32_e32 v67, 1.0, v67
	v_rcp_f32_e32 v60, v60
	v_rcp_f32_e32 v61, v61
	v_add_f32_e32 v62, 1.0, v62
	v_add_f32_e32 v63, 1.0, v63
	v_rcp_f32_e32 v64, v64
	v_rcp_f32_e32 v65, v65
	v_rcp_f32_e32 v66, v66
	v_rcp_f32_e32 v67, v67
	v_rcp_f32_e32 v62, v62
	v_rcp_f32_e32 v63, v63
	v_add_f32_e32 v56, 1.0, v56
	v_add_f32_e32 v57, 1.0, v57
	v_add_f32_e32 v58, 1.0, v58
	v_add_f32_e32 v59, 1.0, v59
	v_add_f32_e32 v52, 1.0, v52
	v_rcp_f32_e32 v56, v56
	v_rcp_f32_e32 v57, v57
	v_rcp_f32_e32 v58, v58
	v_rcp_f32_e32 v59, v59
	v_rcp_f32_e32 v71, v52
	v_cvt_pk_bf16_f32 v54, v60, v61
	v_add_co_u32_e32 v60, vcc, s70, v224
	v_cvt_pk_bf16_f32 v52, v64, v65
	v_cvt_pk_bf16_f32 v53, v66, v67
	v_cvt_pk_bf16_f32 v55, v62, v63
	v_addc_co_u32_e32 v61, vcc, 0, v225, vcc
	global_load_dwordx4 v[124:127], v[140:141], off offset:-128
	global_load_dwordx4 v[128:131], v[140:141], off offset:-64
	global_load_dwordx4 v[132:135], v[140:141], off
	global_load_dwordx4 v[136:139], v[140:141], off offset:64
	s_nop 0
	global_load_dwordx4 v[140:143], v[140:141], off offset:128
	s_nop 0
	global_load_dwordx4 v[144:147], v[160:161], off offset:-128
	global_load_dwordx4 v[148:151], v[160:161], off offset:-64
	global_load_dwordx4 v[152:155], v[160:161], off
	global_load_dwordx4 v[156:159], v[160:161], off offset:64
	s_nop 0
	global_load_dwordx4 v[160:163], v[160:161], off offset:128
	global_store_dwordx4 v[60:61], v[52:55], off
	s_waitcnt vmcnt(5)
	v_mfma_f32_16x16x32_bf16 v[64:67], v[144:147], v[32:35], 0
	v_cvt_pk_bf16_f32 v52, v56, v57
	v_cvt_pk_bf16_f32 v53, v58, v59
	v_cvt_pk_bf16_f32 v54, v68, v69
	v_cvt_pk_bf16_f32 v55, v70, v71
	global_store_dwordx4 v[60:61], v[52:55], off offset:16
	v_mfma_f32_16x16x32_bf16 v[56:59], v[104:107], v[32:35], 0
	v_or_b32_e32 v68, s5, v227
	v_add_u32_e32 v70, s5, v164
	v_ashrrev_i32_e32 v69, 31, v68
	v_mfma_f32_16x16x32_bf16 v[52:55], v[84:87], v[32:35], 0
	v_ashrrev_i32_e32 v71, 31, v70
	v_lshlrev_b64 v[68:69], 7, v[68:69]
	v_mfma_f32_16x16x32_bf16 v[52:55], v[88:91], v[36:39], v[52:55]
	v_lshl_add_u64 v[88:89], v[70:71], 2, s[42:43]
	v_lshl_add_u64 v[206:207], v[206:207], 0, s[22:23]
	v_lshl_add_u64 v[222:223], v[222:223], 0, s[18:19]
	v_mfma_f32_16x16x32_bf16 v[52:55], v[92:95], v[40:43], v[52:55]
	s_mov_b32 s10, s4
	v_mfma_f32_16x16x32_bf16 v[56:59], v[108:111], v[36:39], v[56:59]
	v_mfma_f32_16x16x32_bf16 v[52:55], v[96:99], v[44:47], v[52:55]
	v_mfma_f32_16x16x32_bf16 v[56:59], v[112:115], v[40:43], v[56:59]
	v_lshl_add_u64 v[112:113], v[168:169], 0, v[68:69]
	v_mfma_f32_16x16x32_bf16 v[52:55], v[100:103], v[48:51], v[52:55]
	global_load_dwordx4 v[76:79], v[112:113], off
	global_load_dwordx4 v[80:83], v[112:113], off offset:64
	global_load_dwordx4 v[68:71], v[88:89], off offset:48
	global_load_dwordx4 v[72:75], v[88:89], off offset:32
	global_load_dwordx4 v[84:87], v[88:89], off offset:16
	global_load_dwordx4 v[96:99], v[88:89], off
	s_nop 0
	global_load_dwordx4 v[88:91], v[112:113], off offset:512
	global_load_dwordx4 v[92:95], v[112:113], off offset:576
	global_load_dwordx4 v[100:103], v[112:113], off offset:1024
	global_load_dwordx4 v[104:107], v[112:113], off offset:1088
	global_load_dwordx4 v[108:111], v[112:113], off offset:1536
	s_nop 0
	global_load_dwordx4 v[112:115], v[112:113], off offset:1600
	v_cvt_pk_bf16_f32 v52, v52, v53
	v_mfma_f32_16x16x32_bf16 v[60:63], v[124:127], v[32:35], 0
	v_cvt_pk_bf16_f32 v53, v54, v55
	v_mfma_f32_16x16x32_bf16 v[60:63], v[128:131], v[36:39], v[60:63]
	s_waitcnt vmcnt(17)
	v_mfma_f32_16x16x32_bf16 v[64:67], v[148:151], v[36:39], v[64:67]
	v_mfma_f32_16x16x32_bf16 v[60:63], v[132:135], v[40:43], v[60:63]
	s_waitcnt vmcnt(16)
	v_mfma_f32_16x16x32_bf16 v[64:67], v[152:155], v[40:43], v[64:67]
	v_mfma_f32_16x16x32_bf16 v[56:59], v[116:119], v[44:47], v[56:59]
	v_lshl_add_u64 v[116:117], v[190:191], 1, v[192:193]
	v_add_u32_e32 v190, 64, v190
	v_mfma_f32_16x16x32_bf16 v[60:63], v[136:139], v[44:47], v[60:63]
	s_waitcnt vmcnt(15)
	v_mfma_f32_16x16x32_bf16 v[64:67], v[156:159], v[44:47], v[64:67]
	v_mfma_f32_16x16x32_bf16 v[56:59], v[120:123], v[48:51], v[56:59]
	v_mfma_f32_16x16x32_bf16 v[60:63], v[140:143], v[48:51], v[60:63]
	s_waitcnt vmcnt(14)
	v_mfma_f32_16x16x32_bf16 v[64:67], v[160:163], v[48:51], v[64:67]
	s_nop 4
	v_cvt_pk_bf16_f32 v54, v56, v57
	v_cvt_pk_bf16_f32 v55, v58, v59
	global_store_dwordx4 v[116:117], v[52:55], off
	s_nop 1
	v_cvt_pk_bf16_f32 v52, v60, v61
	v_cvt_pk_bf16_f32 v53, v62, v63
	v_cvt_pk_bf16_f32 v54, v64, v65
	v_cvt_pk_bf16_f32 v55, v66, v67
	global_store_dwordx4 v[116:117], v[52:55], off offset:16
	s_cbranch_scc0 .LBB0_454
	s_add_i32 s54, s54, s55
	s_cmpk_lg_i32 s55, 0x800
	s_cbranch_scc1 .Llora_rot_ok
	s_addk_i32 s54, 0x200
	s_cmpk_lt_i32 s54, 0x1000
	s_cbranch_scc1 .Llora_rot_ok
	s_sub_i32 s54, s54, s55
.Llora_rot_ok:
	s_cmp_ge_i32 s54, s57
	s_cbranch_scc0 .LBB0_453
